# speedup vs baseline: 1.0151x; 1.0038x over previous
; __device__ __forceinline__ float silu_f(float v) { return v * __builtin_amdgcn_rcpf(1.f + __expf(-v)); }
; __device__ __forceinline__ void gemm_tile(const TileDesc& td, char* shm_c, const int wv) {
;     ...
;   if (mode == EPI_PLAIN || mode == EPI_SILU) {
;     #pragma unroll
;     for (int ai = 0; ai < 2; ++ai)
;     #pragma unroll
;     for (int bj = 0; bj < 2; ++bj)
;     #pragma unroll
;     for (int m = 0; m < 4; ++m)
;     #pragma unroll
;     for (int n = 0; n < 2; ++n) {
;       f32x4 v = acc[ai][bj][m][n];
;       if (mode == EPI_SILU) { v[0] = silu_f(v[0]); v[1] = silu_f(v[1]); v[2] = silu_f(v[2]); v[3] = silu_f(v[3]); }
;       long o = (long)(td.bcol + bj * 128 + n * 16 + br_l) * td.ldo + (td.brow + ai * 128 + m * 16 + ar_l);
;       uint2 pk; pk.x = pack2(v[0], v[1]); pk.y = pack2(v[2], v[3]);
;       *(uint2*)(td.outb + o) = pk;
;     }
.LBB0_261:
	s_cmp_eq_u64 s[34:35], 0
	s_cbranch_scc1 .Lg0_ps_store
	v_mul_f32_e32 v146, 0xbfb8aa3b, v124
	v_mul_f32_e32 v147, 0xbfb8aa3b, v125
	v_mul_f32_e32 v148, 0xbfb8aa3b, v126
	v_mul_f32_e32 v149, 0xbfb8aa3b, v127
	v_exp_f32_e32 v146, v146
	v_exp_f32_e32 v147, v147
	v_exp_f32_e32 v148, v148
	v_exp_f32_e32 v149, v149
	v_add_f32_e32 v146, 1.0, v146
	v_add_f32_e32 v147, 1.0, v147
	v_add_f32_e32 v148, 1.0, v148
	v_add_f32_e32 v149, 1.0, v149
	v_rcp_f32_e32 v146, v146
	v_rcp_f32_e32 v147, v147
	v_rcp_f32_e32 v148, v148
	v_rcp_f32_e32 v149, v149
	s_nop 0
	v_pk_mul_f32 v[124:125], v[124:125], v[146:147]
	v_pk_mul_f32 v[126:127], v[126:127], v[148:149]
	v_mul_f32_e32 v146, 0xbfb8aa3b, v116
	v_mul_f32_e32 v147, 0xbfb8aa3b, v117
	v_mul_f32_e32 v148, 0xbfb8aa3b, v118
	v_mul_f32_e32 v149, 0xbfb8aa3b, v119
	v_exp_f32_e32 v146, v146
	v_exp_f32_e32 v147, v147
	v_exp_f32_e32 v148, v148
	v_exp_f32_e32 v149, v149
	v_add_f32_e32 v146, 1.0, v146
	v_add_f32_e32 v147, 1.0, v147
	v_add_f32_e32 v148, 1.0, v148
	v_add_f32_e32 v149, 1.0, v149
	v_rcp_f32_e32 v146, v146
	v_rcp_f32_e32 v147, v147
	v_rcp_f32_e32 v148, v148
	v_rcp_f32_e32 v149, v149
	s_nop 0
	v_pk_mul_f32 v[116:117], v[116:117], v[146:147]
	v_pk_mul_f32 v[118:119], v[118:119], v[148:149]
	v_mul_f32_e32 v146, 0xbfb8aa3b, v108
	v_mul_f32_e32 v147, 0xbfb8aa3b, v109
	v_mul_f32_e32 v148, 0xbfb8aa3b, v110
	v_mul_f32_e32 v149, 0xbfb8aa3b, v111
	v_exp_f32_e32 v146, v146
	v_exp_f32_e32 v147, v147
	v_exp_f32_e32 v148, v148
	v_exp_f32_e32 v149, v149
	v_add_f32_e32 v146, 1.0, v146
	v_add_f32_e32 v147, 1.0, v147
	v_add_f32_e32 v148, 1.0, v148
	v_add_f32_e32 v149, 1.0, v149
	v_rcp_f32_e32 v146, v146
	v_rcp_f32_e32 v147, v147
	v_rcp_f32_e32 v148, v148
	v_rcp_f32_e32 v149, v149
	s_nop 0
	v_pk_mul_f32 v[108:109], v[108:109], v[146:147]
	v_pk_mul_f32 v[110:111], v[110:111], v[148:149]
	v_mul_f32_e32 v146, 0xbfb8aa3b, v100
	v_mul_f32_e32 v147, 0xbfb8aa3b, v101
	v_mul_f32_e32 v148, 0xbfb8aa3b, v102
	v_mul_f32_e32 v149, 0xbfb8aa3b, v103
	v_exp_f32_e32 v146, v146
	v_exp_f32_e32 v147, v147
	v_exp_f32_e32 v148, v148
	v_exp_f32_e32 v149, v149
	v_add_f32_e32 v146, 1.0, v146
	v_add_f32_e32 v147, 1.0, v147
	v_add_f32_e32 v148, 1.0, v148
	v_add_f32_e32 v149, 1.0, v149
	v_rcp_f32_e32 v146, v146
	v_rcp_f32_e32 v147, v147
	v_rcp_f32_e32 v148, v148
	v_rcp_f32_e32 v149, v149
	s_nop 0
	v_pk_mul_f32 v[100:101], v[100:101], v[146:147]
	v_pk_mul_f32 v[102:103], v[102:103], v[148:149]
	v_mul_f32_e32 v146, 0xbfb8aa3b, v120
	v_mul_f32_e32 v147, 0xbfb8aa3b, v121
	v_mul_f32_e32 v148, 0xbfb8aa3b, v122
	v_mul_f32_e32 v149, 0xbfb8aa3b, v123
	v_exp_f32_e32 v146, v146
	v_exp_f32_e32 v147, v147
	v_exp_f32_e32 v148, v148
	v_exp_f32_e32 v149, v149
	v_add_f32_e32 v146, 1.0, v146
	v_add_f32_e32 v147, 1.0, v147
	v_add_f32_e32 v148, 1.0, v148
	v_add_f32_e32 v149, 1.0, v149
	v_rcp_f32_e32 v146, v146
	v_rcp_f32_e32 v147, v147
	v_rcp_f32_e32 v148, v148
	v_rcp_f32_e32 v149, v149
	s_nop 0
	v_pk_mul_f32 v[120:121], v[120:121], v[146:147]
	v_pk_mul_f32 v[122:123], v[122:123], v[148:149]
	v_mul_f32_e32 v146, 0xbfb8aa3b, v112
	v_mul_f32_e32 v147, 0xbfb8aa3b, v113
	v_mul_f32_e32 v148, 0xbfb8aa3b, v114
	v_mul_f32_e32 v149, 0xbfb8aa3b, v115
	v_exp_f32_e32 v146, v146
	v_exp_f32_e32 v147, v147
	v_exp_f32_e32 v148, v148
	v_exp_f32_e32 v149, v149
	v_add_f32_e32 v146, 1.0, v146
	v_add_f32_e32 v147, 1.0, v147
	v_add_f32_e32 v148, 1.0, v148
	v_add_f32_e32 v149, 1.0, v149
	v_rcp_f32_e32 v146, v146
	v_rcp_f32_e32 v147, v147
	v_rcp_f32_e32 v148, v148
	v_rcp_f32_e32 v149, v149
	s_nop 0
	v_pk_mul_f32 v[112:113], v[112:113], v[146:147]
	v_pk_mul_f32 v[114:115], v[114:115], v[148:149]
	v_mul_f32_e32 v146, 0xbfb8aa3b, v104
	v_mul_f32_e32 v147, 0xbfb8aa3b, v105
	v_mul_f32_e32 v148, 0xbfb8aa3b, v106
	v_mul_f32_e32 v149, 0xbfb8aa3b, v107
	v_exp_f32_e32 v146, v146
	v_exp_f32_e32 v147, v147
	v_exp_f32_e32 v148, v148
	v_exp_f32_e32 v149, v149
	v_add_f32_e32 v146, 1.0, v146
	v_add_f32_e32 v147, 1.0, v147
	v_add_f32_e32 v148, 1.0, v148
	v_add_f32_e32 v149, 1.0, v149
	v_rcp_f32_e32 v146, v146
	v_rcp_f32_e32 v147, v147
	v_rcp_f32_e32 v148, v148
	v_rcp_f32_e32 v149, v149
	s_nop 0
	v_pk_mul_f32 v[104:105], v[104:105], v[146:147]
	v_pk_mul_f32 v[106:107], v[106:107], v[148:149]
	v_mul_f32_e32 v146, 0xbfb8aa3b, v92
	v_mul_f32_e32 v147, 0xbfb8aa3b, v93
	v_mul_f32_e32 v148, 0xbfb8aa3b, v94
	v_mul_f32_e32 v149, 0xbfb8aa3b, v95
	v_exp_f32_e32 v146, v146
	v_exp_f32_e32 v147, v147
	v_exp_f32_e32 v148, v148
	v_exp_f32_e32 v149, v149
	v_add_f32_e32 v146, 1.0, v146
	v_add_f32_e32 v147, 1.0, v147
	v_add_f32_e32 v148, 1.0, v148
	v_add_f32_e32 v149, 1.0, v149
	v_rcp_f32_e32 v146, v146
	v_rcp_f32_e32 v147, v147
	v_rcp_f32_e32 v148, v148
	v_rcp_f32_e32 v149, v149
	s_nop 0
	v_pk_mul_f32 v[92:93], v[92:93], v[146:147]
	v_pk_mul_f32 v[94:95], v[94:95], v[148:149]
	v_mul_f32_e32 v146, 0xbfb8aa3b, v96
	v_mul_f32_e32 v147, 0xbfb8aa3b, v97
	v_mul_f32_e32 v148, 0xbfb8aa3b, v98
	v_mul_f32_e32 v149, 0xbfb8aa3b, v99
	v_exp_f32_e32 v146, v146
	v_exp_f32_e32 v147, v147
	v_exp_f32_e32 v148, v148
	v_exp_f32_e32 v149, v149
	v_add_f32_e32 v146, 1.0, v146
	v_add_f32_e32 v147, 1.0, v147
	v_add_f32_e32 v148, 1.0, v148
	v_add_f32_e32 v149, 1.0, v149
	v_rcp_f32_e32 v146, v146
	v_rcp_f32_e32 v147, v147
	v_rcp_f32_e32 v148, v148
	v_rcp_f32_e32 v149, v149
	s_nop 0
	v_pk_mul_f32 v[96:97], v[96:97], v[146:147]
	v_pk_mul_f32 v[98:99], v[98:99], v[148:149]
	v_mul_f32_e32 v146, 0xbfb8aa3b, v84
	v_mul_f32_e32 v147, 0xbfb8aa3b, v85
	v_mul_f32_e32 v148, 0xbfb8aa3b, v86
	v_mul_f32_e32 v149, 0xbfb8aa3b, v87
	v_exp_f32_e32 v146, v146
	v_exp_f32_e32 v147, v147
	v_exp_f32_e32 v148, v148
	v_exp_f32_e32 v149, v149
	v_add_f32_e32 v146, 1.0, v146
; __device__ __forceinline__ float silu_f(float v) { return v * __builtin_amdgcn_rcpf(1.f + __expf(-v)); }
; __device__ __forceinline__ void gemm_tile(const TileDesc& td, char* shm_c, const int wv) {
;     ...
;     for (int m = 0; m < 4; ++m)
;     #pragma unroll
;     for (int n = 0; n < 2; ++n) {
;       f32x4 v = acc[ai][bj][m][n];
;       if (mode == EPI_SILU) { v[0] = silu_f(v[0]); v[1] = silu_f(v[1]); v[2] = silu_f(v[2]); v[3] = silu_f(v[3]); }
	v_add_f32_e32 v147, 1.0, v147
	v_add_f32_e32 v148, 1.0, v148
	v_add_f32_e32 v149, 1.0, v149
	v_rcp_f32_e32 v146, v146
	v_rcp_f32_e32 v147, v147
	v_rcp_f32_e32 v148, v148
	v_rcp_f32_e32 v149, v149
	s_nop 0
	v_pk_mul_f32 v[84:85], v[84:85], v[146:147]
	v_pk_mul_f32 v[86:87], v[86:87], v[148:149]
	v_mul_f32_e32 v146, 0xbfb8aa3b, v76
	v_mul_f32_e32 v147, 0xbfb8aa3b, v77
	v_mul_f32_e32 v148, 0xbfb8aa3b, v78
	v_mul_f32_e32 v149, 0xbfb8aa3b, v79
	v_exp_f32_e32 v146, v146
	v_exp_f32_e32 v147, v147
	v_exp_f32_e32 v148, v148
	v_exp_f32_e32 v149, v149
	v_add_f32_e32 v146, 1.0, v146
	v_add_f32_e32 v147, 1.0, v147
	v_add_f32_e32 v148, 1.0, v148
	v_add_f32_e32 v149, 1.0, v149
	v_rcp_f32_e32 v146, v146
	v_rcp_f32_e32 v147, v147
	v_rcp_f32_e32 v148, v148
	v_rcp_f32_e32 v149, v149
	s_nop 0
	v_pk_mul_f32 v[76:77], v[76:77], v[146:147]
	v_pk_mul_f32 v[78:79], v[78:79], v[148:149]
	v_mul_f32_e32 v146, 0xbfb8aa3b, v68
	v_mul_f32_e32 v147, 0xbfb8aa3b, v69
	v_mul_f32_e32 v148, 0xbfb8aa3b, v70
	v_mul_f32_e32 v149, 0xbfb8aa3b, v71
	v_exp_f32_e32 v146, v146
	v_exp_f32_e32 v147, v147
	v_exp_f32_e32 v148, v148
	v_exp_f32_e32 v149, v149
	v_add_f32_e32 v146, 1.0, v146
	v_add_f32_e32 v147, 1.0, v147
	v_add_f32_e32 v148, 1.0, v148
	v_add_f32_e32 v149, 1.0, v149
	v_rcp_f32_e32 v146, v146
	v_rcp_f32_e32 v147, v147
	v_rcp_f32_e32 v148, v148
	v_rcp_f32_e32 v149, v149
	s_nop 0
	v_pk_mul_f32 v[68:69], v[68:69], v[146:147]
	v_pk_mul_f32 v[70:71], v[70:71], v[148:149]
	v_mul_f32_e32 v146, 0xbfb8aa3b, v88
	v_mul_f32_e32 v147, 0xbfb8aa3b, v89
	v_mul_f32_e32 v148, 0xbfb8aa3b, v90
	v_mul_f32_e32 v149, 0xbfb8aa3b, v91
	v_exp_f32_e32 v146, v146
	v_exp_f32_e32 v147, v147
	v_exp_f32_e32 v148, v148
	v_exp_f32_e32 v149, v149
	v_add_f32_e32 v146, 1.0, v146
	v_add_f32_e32 v147, 1.0, v147
	v_add_f32_e32 v148, 1.0, v148
	v_add_f32_e32 v149, 1.0, v149
	v_rcp_f32_e32 v146, v146
	v_rcp_f32_e32 v147, v147
	v_rcp_f32_e32 v148, v148
	v_rcp_f32_e32 v149, v149
	s_nop 0
	v_pk_mul_f32 v[88:89], v[88:89], v[146:147]
	v_pk_mul_f32 v[90:91], v[90:91], v[148:149]
	v_mul_f32_e32 v146, 0xbfb8aa3b, v80
	v_mul_f32_e32 v147, 0xbfb8aa3b, v81
	v_mul_f32_e32 v148, 0xbfb8aa3b, v82
	v_mul_f32_e32 v149, 0xbfb8aa3b, v83
	v_exp_f32_e32 v146, v146
	v_exp_f32_e32 v147, v147
	v_exp_f32_e32 v148, v148
	v_exp_f32_e32 v149, v149
	v_add_f32_e32 v146, 1.0, v146
	v_add_f32_e32 v147, 1.0, v147
	v_add_f32_e32 v148, 1.0, v148
	v_add_f32_e32 v149, 1.0, v149
	v_rcp_f32_e32 v146, v146
	v_rcp_f32_e32 v147, v147
	v_rcp_f32_e32 v148, v148
	v_rcp_f32_e32 v149, v149
	s_nop 0
	v_pk_mul_f32 v[80:81], v[80:81], v[146:147]
	v_pk_mul_f32 v[82:83], v[82:83], v[148:149]
	v_mul_f32_e32 v146, 0xbfb8aa3b, v72
	v_mul_f32_e32 v147, 0xbfb8aa3b, v73
	v_mul_f32_e32 v148, 0xbfb8aa3b, v74
	v_mul_f32_e32 v149, 0xbfb8aa3b, v75
	v_exp_f32_e32 v146, v146
	v_exp_f32_e32 v147, v147
	v_exp_f32_e32 v148, v148
	v_exp_f32_e32 v149, v149
	v_add_f32_e32 v146, 1.0, v146
	v_add_f32_e32 v147, 1.0, v147
	v_add_f32_e32 v148, 1.0, v148
	v_add_f32_e32 v149, 1.0, v149
	v_rcp_f32_e32 v146, v146
	v_rcp_f32_e32 v147, v147
	v_rcp_f32_e32 v148, v148
	v_rcp_f32_e32 v149, v149
	s_nop 0
	v_pk_mul_f32 v[72:73], v[72:73], v[146:147]
	v_pk_mul_f32 v[74:75], v[74:75], v[148:149]
	v_mul_f32_e32 v146, 0xbfb8aa3b, v64
	v_mul_f32_e32 v147, 0xbfb8aa3b, v65
	v_mul_f32_e32 v148, 0xbfb8aa3b, v66
	v_mul_f32_e32 v149, 0xbfb8aa3b, v67
	v_exp_f32_e32 v146, v146
	v_exp_f32_e32 v147, v147
	v_exp_f32_e32 v148, v148
	v_exp_f32_e32 v149, v149
	v_add_f32_e32 v146, 1.0, v146
	v_add_f32_e32 v147, 1.0, v147
	v_add_f32_e32 v148, 1.0, v148
	v_add_f32_e32 v149, 1.0, v149
	v_rcp_f32_e32 v146, v146
	v_rcp_f32_e32 v147, v147
	v_rcp_f32_e32 v148, v148
	v_rcp_f32_e32 v149, v149
	s_nop 0
	v_pk_mul_f32 v[64:65], v[64:65], v[146:147]
	v_pk_mul_f32 v[66:67], v[66:67], v[148:149]
	v_mul_f32_e32 v146, 0xbfb8aa3b, v60
	v_mul_f32_e32 v147, 0xbfb8aa3b, v61
	v_mul_f32_e32 v148, 0xbfb8aa3b, v62
	v_mul_f32_e32 v149, 0xbfb8aa3b, v63
	v_exp_f32_e32 v146, v146
	v_exp_f32_e32 v147, v147
	v_exp_f32_e32 v148, v148
	v_exp_f32_e32 v149, v149
	v_add_f32_e32 v146, 1.0, v146
	v_add_f32_e32 v147, 1.0, v147
	v_add_f32_e32 v148, 1.0, v148
	v_add_f32_e32 v149, 1.0, v149
	v_rcp_f32_e32 v146, v146
	v_rcp_f32_e32 v147, v147
	v_rcp_f32_e32 v148, v148
	v_rcp_f32_e32 v149, v149
	s_nop 0
	v_pk_mul_f32 v[60:61], v[60:61], v[146:147]
	v_pk_mul_f32 v[62:63], v[62:63], v[148:149]
	v_mul_f32_e32 v146, 0xbfb8aa3b, v52
	v_mul_f32_e32 v147, 0xbfb8aa3b, v53
	v_mul_f32_e32 v148, 0xbfb8aa3b, v54
	v_mul_f32_e32 v149, 0xbfb8aa3b, v55
	v_exp_f32_e32 v146, v146
	v_exp_f32_e32 v147, v147
	v_exp_f32_e32 v148, v148
	v_exp_f32_e32 v149, v149
	v_add_f32_e32 v146, 1.0, v146
	v_add_f32_e32 v147, 1.0, v147
	v_add_f32_e32 v148, 1.0, v148
	v_add_f32_e32 v149, 1.0, v149
	v_rcp_f32_e32 v146, v146
	v_rcp_f32_e32 v147, v147
	v_rcp_f32_e32 v148, v148
	v_rcp_f32_e32 v149, v149
	s_nop 0
	v_pk_mul_f32 v[52:53], v[52:53], v[146:147]
	v_pk_mul_f32 v[54:55], v[54:55], v[148:149]
	v_mul_f32_e32 v146, 0xbfb8aa3b, v44
	v_mul_f32_e32 v147, 0xbfb8aa3b, v45
	v_mul_f32_e32 v148, 0xbfb8aa3b, v46
	v_mul_f32_e32 v149, 0xbfb8aa3b, v47
	v_exp_f32_e32 v146, v146
	v_exp_f32_e32 v147, v147
	v_exp_f32_e32 v148, v148
	v_exp_f32_e32 v149, v149
	v_add_f32_e32 v146, 1.0, v146
	v_add_f32_e32 v147, 1.0, v147
	v_add_f32_e32 v148, 1.0, v148
	v_add_f32_e32 v149, 1.0, v149
	v_rcp_f32_e32 v146, v146
	v_rcp_f32_e32 v147, v147
	v_rcp_f32_e32 v148, v148
	v_rcp_f32_e32 v149, v149
	s_nop 0
	v_pk_mul_f32 v[44:45], v[44:45], v[146:147]
	v_pk_mul_f32 v[46:47], v[46:47], v[148:149]
	v_mul_f32_e32 v146, 0xbfb8aa3b, v36
	v_mul_f32_e32 v147, 0xbfb8aa3b, v37
	v_mul_f32_e32 v148, 0xbfb8aa3b, v38
	v_mul_f32_e32 v149, 0xbfb8aa3b, v39
; __device__ __forceinline__ float silu_f(float v) { return v * __builtin_amdgcn_rcpf(1.f + __expf(-v)); }
; __device__ __forceinline__ void gemm_tile(const TileDesc& td, char* shm_c, const int wv) {
;     ...
;     for (int m = 0; m < 4; ++m)
;     #pragma unroll
;     for (int n = 0; n < 2; ++n) {
;       f32x4 v = acc[ai][bj][m][n];
;       if (mode == EPI_SILU) { v[0] = silu_f(v[0]); v[1] = silu_f(v[1]); v[2] = silu_f(v[2]); v[3] = silu_f(v[3]); }
	v_exp_f32_e32 v146, v146
	v_exp_f32_e32 v147, v147
	v_exp_f32_e32 v148, v148
	v_exp_f32_e32 v149, v149
	v_add_f32_e32 v146, 1.0, v146
	v_add_f32_e32 v147, 1.0, v147
	v_add_f32_e32 v148, 1.0, v148
	v_add_f32_e32 v149, 1.0, v149
	v_rcp_f32_e32 v146, v146
	v_rcp_f32_e32 v147, v147
	v_rcp_f32_e32 v148, v148
	v_rcp_f32_e32 v149, v149
	s_nop 0
	v_pk_mul_f32 v[36:37], v[36:37], v[146:147]
	v_pk_mul_f32 v[38:39], v[38:39], v[148:149]
	v_mul_f32_e32 v146, 0xbfb8aa3b, v56
	v_mul_f32_e32 v147, 0xbfb8aa3b, v57
	v_mul_f32_e32 v148, 0xbfb8aa3b, v58
	v_mul_f32_e32 v149, 0xbfb8aa3b, v59
	v_exp_f32_e32 v146, v146
	v_exp_f32_e32 v147, v147
	v_exp_f32_e32 v148, v148
	v_exp_f32_e32 v149, v149
	v_add_f32_e32 v146, 1.0, v146
	v_add_f32_e32 v147, 1.0, v147
	v_add_f32_e32 v148, 1.0, v148
	v_add_f32_e32 v149, 1.0, v149
	v_rcp_f32_e32 v146, v146
	v_rcp_f32_e32 v147, v147
	v_rcp_f32_e32 v148, v148
	v_rcp_f32_e32 v149, v149
	s_nop 0
	v_pk_mul_f32 v[56:57], v[56:57], v[146:147]
	v_pk_mul_f32 v[58:59], v[58:59], v[148:149]
	v_mul_f32_e32 v146, 0xbfb8aa3b, v48
	v_mul_f32_e32 v147, 0xbfb8aa3b, v49
	v_mul_f32_e32 v148, 0xbfb8aa3b, v50
	v_mul_f32_e32 v149, 0xbfb8aa3b, v51
	v_exp_f32_e32 v146, v146
	v_exp_f32_e32 v147, v147
	v_exp_f32_e32 v148, v148
	v_exp_f32_e32 v149, v149
	v_add_f32_e32 v146, 1.0, v146
	v_add_f32_e32 v147, 1.0, v147
	v_add_f32_e32 v148, 1.0, v148
	v_add_f32_e32 v149, 1.0, v149
	v_rcp_f32_e32 v146, v146
	v_rcp_f32_e32 v147, v147
	v_rcp_f32_e32 v148, v148
	v_rcp_f32_e32 v149, v149
	s_nop 0
	v_pk_mul_f32 v[48:49], v[48:49], v[146:147]
	v_pk_mul_f32 v[50:51], v[50:51], v[148:149]
	v_mul_f32_e32 v146, 0xbfb8aa3b, v40
	v_mul_f32_e32 v147, 0xbfb8aa3b, v41
	v_mul_f32_e32 v148, 0xbfb8aa3b, v42
	v_mul_f32_e32 v149, 0xbfb8aa3b, v43
	v_exp_f32_e32 v146, v146
	v_exp_f32_e32 v147, v147
	v_exp_f32_e32 v148, v148
	v_exp_f32_e32 v149, v149
	v_add_f32_e32 v146, 1.0, v146
	v_add_f32_e32 v147, 1.0, v147
	v_add_f32_e32 v148, 1.0, v148
	v_add_f32_e32 v149, 1.0, v149
	v_rcp_f32_e32 v146, v146
	v_rcp_f32_e32 v147, v147
	v_rcp_f32_e32 v148, v148
	v_rcp_f32_e32 v149, v149
	s_nop 0
	v_pk_mul_f32 v[40:41], v[40:41], v[146:147]
	v_pk_mul_f32 v[42:43], v[42:43], v[148:149]
	v_mul_f32_e32 v146, 0xbfb8aa3b, v28
	v_mul_f32_e32 v147, 0xbfb8aa3b, v29
	v_mul_f32_e32 v148, 0xbfb8aa3b, v30
	v_mul_f32_e32 v149, 0xbfb8aa3b, v31
	v_exp_f32_e32 v146, v146
	v_exp_f32_e32 v147, v147
	v_exp_f32_e32 v148, v148
	v_exp_f32_e32 v149, v149
	v_add_f32_e32 v146, 1.0, v146
	v_add_f32_e32 v147, 1.0, v147
	v_add_f32_e32 v148, 1.0, v148
	v_add_f32_e32 v149, 1.0, v149
	v_rcp_f32_e32 v146, v146
	v_rcp_f32_e32 v147, v147
	v_rcp_f32_e32 v148, v148
	v_rcp_f32_e32 v149, v149
	s_nop 0
	v_pk_mul_f32 v[28:29], v[28:29], v[146:147]
	v_pk_mul_f32 v[30:31], v[30:31], v[148:149]
	v_mul_f32_e32 v146, 0xbfb8aa3b, v32
	v_mul_f32_e32 v147, 0xbfb8aa3b, v33
	v_mul_f32_e32 v148, 0xbfb8aa3b, v34
	v_mul_f32_e32 v149, 0xbfb8aa3b, v35
	v_exp_f32_e32 v146, v146
	v_exp_f32_e32 v147, v147
	v_exp_f32_e32 v148, v148
	v_exp_f32_e32 v149, v149
	v_add_f32_e32 v146, 1.0, v146
	v_add_f32_e32 v147, 1.0, v147
	v_add_f32_e32 v148, 1.0, v148
	v_add_f32_e32 v149, 1.0, v149
	v_rcp_f32_e32 v146, v146
	v_rcp_f32_e32 v147, v147
	v_rcp_f32_e32 v148, v148
	v_rcp_f32_e32 v149, v149
	s_nop 0
	v_pk_mul_f32 v[32:33], v[32:33], v[146:147]
	v_pk_mul_f32 v[34:35], v[34:35], v[148:149]
	v_mul_f32_e32 v146, 0xbfb8aa3b, v20
	v_mul_f32_e32 v147, 0xbfb8aa3b, v21
	v_mul_f32_e32 v148, 0xbfb8aa3b, v22
	v_mul_f32_e32 v149, 0xbfb8aa3b, v23
	v_exp_f32_e32 v146, v146
	v_exp_f32_e32 v147, v147
	v_exp_f32_e32 v148, v148
	v_exp_f32_e32 v149, v149
	v_add_f32_e32 v146, 1.0, v146
	v_add_f32_e32 v147, 1.0, v147
	v_add_f32_e32 v148, 1.0, v148
	v_add_f32_e32 v149, 1.0, v149
	v_rcp_f32_e32 v146, v146
	v_rcp_f32_e32 v147, v147
	v_rcp_f32_e32 v148, v148
	v_rcp_f32_e32 v149, v149
	s_nop 0
	v_pk_mul_f32 v[20:21], v[20:21], v[146:147]
	v_pk_mul_f32 v[22:23], v[22:23], v[148:149]
	v_mul_f32_e32 v146, 0xbfb8aa3b, v12
	v_mul_f32_e32 v147, 0xbfb8aa3b, v13
	v_mul_f32_e32 v148, 0xbfb8aa3b, v14
	v_mul_f32_e32 v149, 0xbfb8aa3b, v15
	v_exp_f32_e32 v146, v146
	v_exp_f32_e32 v147, v147
	v_exp_f32_e32 v148, v148
	v_exp_f32_e32 v149, v149
	v_add_f32_e32 v146, 1.0, v146
	v_add_f32_e32 v147, 1.0, v147
	v_add_f32_e32 v148, 1.0, v148
	v_add_f32_e32 v149, 1.0, v149
	v_rcp_f32_e32 v146, v146
	v_rcp_f32_e32 v147, v147
	v_rcp_f32_e32 v148, v148
	v_rcp_f32_e32 v149, v149
	s_nop 0
	v_pk_mul_f32 v[12:13], v[12:13], v[146:147]
	v_pk_mul_f32 v[14:15], v[14:15], v[148:149]
	v_mul_f32_e32 v146, 0xbfb8aa3b, v4
	v_mul_f32_e32 v147, 0xbfb8aa3b, v5
	v_mul_f32_e32 v148, 0xbfb8aa3b, v6
	v_mul_f32_e32 v149, 0xbfb8aa3b, v7
	v_exp_f32_e32 v146, v146
	v_exp_f32_e32 v147, v147
	v_exp_f32_e32 v148, v148
	v_exp_f32_e32 v149, v149
	v_add_f32_e32 v146, 1.0, v146
	v_add_f32_e32 v147, 1.0, v147
	v_add_f32_e32 v148, 1.0, v148
	v_add_f32_e32 v149, 1.0, v149
	v_rcp_f32_e32 v146, v146
	v_rcp_f32_e32 v147, v147
	v_rcp_f32_e32 v148, v148
	v_rcp_f32_e32 v149, v149
	s_nop 0
	v_pk_mul_f32 v[4:5], v[4:5], v[146:147]
	v_pk_mul_f32 v[6:7], v[6:7], v[148:149]
	v_mul_f32_e32 v146, 0xbfb8aa3b, v24
	v_mul_f32_e32 v147, 0xbfb8aa3b, v25
	v_mul_f32_e32 v148, 0xbfb8aa3b, v26
	v_mul_f32_e32 v149, 0xbfb8aa3b, v27
	v_exp_f32_e32 v146, v146
	v_exp_f32_e32 v147, v147
	v_exp_f32_e32 v148, v148
	v_exp_f32_e32 v149, v149
	v_add_f32_e32 v146, 1.0, v146
	v_add_f32_e32 v147, 1.0, v147
	v_add_f32_e32 v148, 1.0, v148
	v_add_f32_e32 v149, 1.0, v149
	v_rcp_f32_e32 v146, v146
	v_rcp_f32_e32 v147, v147
	v_rcp_f32_e32 v148, v148
	v_rcp_f32_e32 v149, v149
	s_nop 0
	v_pk_mul_f32 v[24:25], v[24:25], v[146:147]
	v_pk_mul_f32 v[26:27], v[26:27], v[148:149]
; __device__ __forceinline__ float silu_f(float v) { return v * __builtin_amdgcn_rcpf(1.f + __expf(-v)); }
; __device__ __forceinline__ void gemm_tile(const TileDesc& td, char* shm_c, const int wv) {
;     ...
;     for (int m = 0; m < 4; ++m)
;     #pragma unroll
;     for (int n = 0; n < 2; ++n) {
;       f32x4 v = acc[ai][bj][m][n];
;       if (mode == EPI_SILU) { v[0] = silu_f(v[0]); v[1] = silu_f(v[1]); v[2] = silu_f(v[2]); v[3] = silu_f(v[3]); }
	v_mul_f32_e32 v146, 0xbfb8aa3b, v16
	v_mul_f32_e32 v147, 0xbfb8aa3b, v17
	v_mul_f32_e32 v148, 0xbfb8aa3b, v18
	v_mul_f32_e32 v149, 0xbfb8aa3b, v19
	v_exp_f32_e32 v146, v146
	v_exp_f32_e32 v147, v147
	v_exp_f32_e32 v148, v148
	v_exp_f32_e32 v149, v149
	v_add_f32_e32 v146, 1.0, v146
	v_add_f32_e32 v147, 1.0, v147
	v_add_f32_e32 v148, 1.0, v148
	v_add_f32_e32 v149, 1.0, v149
	v_rcp_f32_e32 v146, v146
	v_rcp_f32_e32 v147, v147
	v_rcp_f32_e32 v148, v148
	v_rcp_f32_e32 v149, v149
	s_nop 0
	v_pk_mul_f32 v[16:17], v[16:17], v[146:147]
	v_pk_mul_f32 v[18:19], v[18:19], v[148:149]
	v_mul_f32_e32 v146, 0xbfb8aa3b, v8
	v_mul_f32_e32 v147, 0xbfb8aa3b, v9
	v_mul_f32_e32 v148, 0xbfb8aa3b, v10
	v_mul_f32_e32 v149, 0xbfb8aa3b, v11
	v_exp_f32_e32 v146, v146
	v_exp_f32_e32 v147, v147
	v_exp_f32_e32 v148, v148
	v_exp_f32_e32 v149, v149
	v_add_f32_e32 v146, 1.0, v146
	v_add_f32_e32 v147, 1.0, v147
	v_add_f32_e32 v148, 1.0, v148
	v_add_f32_e32 v149, 1.0, v149
	v_rcp_f32_e32 v146, v146
	v_rcp_f32_e32 v147, v147
	v_rcp_f32_e32 v148, v148
	v_rcp_f32_e32 v149, v149
	s_nop 0
	v_pk_mul_f32 v[8:9], v[8:9], v[146:147]
	v_pk_mul_f32 v[10:11], v[10:11], v[148:149]
	v_mul_f32_e32 v146, 0xbfb8aa3b, v0
	v_mul_f32_e32 v147, 0xbfb8aa3b, v1
	v_mul_f32_e32 v148, 0xbfb8aa3b, v2
	v_mul_f32_e32 v149, 0xbfb8aa3b, v3
	v_exp_f32_e32 v146, v146
	v_exp_f32_e32 v147, v147
	v_exp_f32_e32 v148, v148
	v_exp_f32_e32 v149, v149
	v_add_f32_e32 v146, 1.0, v146
	v_add_f32_e32 v147, 1.0, v147
	v_add_f32_e32 v148, 1.0, v148
	v_add_f32_e32 v149, 1.0, v149
	v_rcp_f32_e32 v146, v146
	v_rcp_f32_e32 v147, v147
	v_rcp_f32_e32 v148, v148
	v_rcp_f32_e32 v149, v149
	s_nop 0
	v_pk_mul_f32 v[0:1], v[0:1], v[146:147]
	v_pk_mul_f32 v[2:3], v[2:3], v[148:149]
; __device__ __forceinline__ float silu_f(float v) { return v * __builtin_amdgcn_rcpf(1.f + __expf(-v)); }
; __device__ __forceinline__ void gemm_tile(const TileDesc& td, char* shm_c, const int wv) {
;     ...
;   if (mode == EPI_PLAIN || mode == EPI_SILU) {
;     #pragma unroll
;     for (int ai = 0; ai < 2; ++ai)
;     #pragma unroll
;     for (int bj = 0; bj < 2; ++bj)
;     #pragma unroll
;     for (int m = 0; m < 4; ++m)
;     #pragma unroll
;     for (int n = 0; n < 2; ++n) {
;       f32x4 v = acc[ai][bj][m][n];
;       if (mode == EPI_SILU) { v[0] = silu_f(v[0]); v[1] = silu_f(v[1]); v[2] = silu_f(v[2]); v[3] = silu_f(v[3]); }
;       long o = (long)(td.bcol + bj * 128 + n * 16 + br_l) * td.ldo + (td.brow + ai * 128 + m * 16 + ar_l);
;       uint2 pk; pk.x = pack2(v[0], v[1]); pk.y = pack2(v[2], v[3]);
;       *(uint2*)(td.outb + o) = pk;
;     }
; __device__ __forceinline__ void gemm_stage(const Params& p, int s, char* smem, const int wv) {
;     ...
;   for (int t = blockIdx.x; t < ntiles; t += gridDim.x) {
.Lg0_ps_store:
	v_mbcnt_lo_u32_b32 v128, -1, 0
	v_mbcnt_hi_u32_b32 v128, -1, v128
	v_and_b32_e32 v150, 16, v128
	v_lshrrev_b32_e32 v151, 1, v150
	v_add_u32_e32 v150, v150, v151
	v_mov_b32_e32 v151, 0
	v_lshrrev_b32_e32 v130, 2, v128
	v_and_or_b32 v128, v128, 15, s40
	v_and_or_b32 v132, v130, 12, s2
	s_lshl_b32 s12, s30, 8
	v_or_b32_e32 v128, s31, v128
	v_add_u32_e32 v130, s12, v132
	v_ashrrev_i32_e32 v131, 31, v130
	v_mov_b32_e32 v152, v128
	v_mul_hi_i32_i24_e32 v155, s28, v152
	v_mul_i32_i24_e32 v154, s28, v152
	v_lshl_add_u64 v[154:155], v[154:155], 1, s[26:27]
	v_lshl_add_u64 v[154:155], v[130:131], 1, v[154:155]
	v_lshl_add_u64 v[156:157], v[154:155], 0, v[150:151]
	v_cvt_pk_bf16_f32 v124, v124, v125
	v_cvt_pk_bf16_f32 v125, v126, v127
	v_cvt_pk_bf16_f32 v126, v116, v117
	v_cvt_pk_bf16_f32 v127, v118, v119
	s_nop 1
	v_permlane16_swap_b32_e32 v124, v126
	v_permlane16_swap_b32_e32 v125, v127
	global_store_dwordx4 v[156:157], v[124:127], off
	v_cvt_pk_bf16_f32 v108, v108, v109
	v_cvt_pk_bf16_f32 v109, v110, v111
	v_cvt_pk_bf16_f32 v110, v100, v101
	v_cvt_pk_bf16_f32 v111, v102, v103
	s_nop 1
	v_permlane16_swap_b32_e32 v108, v110
	v_permlane16_swap_b32_e32 v109, v111
	global_store_dwordx4 v[156:157], v[108:111], off offset:64
	v_cvt_pk_bf16_f32 v60, v60, v61
	v_cvt_pk_bf16_f32 v61, v62, v63
	v_cvt_pk_bf16_f32 v62, v52, v53
	v_cvt_pk_bf16_f32 v63, v54, v55
	s_nop 1
	v_permlane16_swap_b32_e32 v60, v62
	v_permlane16_swap_b32_e32 v61, v63
	global_store_dwordx4 v[156:157], v[60:63], off offset:256
	v_cvt_pk_bf16_f32 v44, v44, v45
	v_cvt_pk_bf16_f32 v45, v46, v47
	v_cvt_pk_bf16_f32 v46, v36, v37
	v_cvt_pk_bf16_f32 v47, v38, v39
	s_nop 1
	v_permlane16_swap_b32_e32 v44, v46
	v_permlane16_swap_b32_e32 v45, v47
	global_store_dwordx4 v[156:157], v[44:47], off offset:320
	v_or_b32_e32 v152, 0x10, v128
	v_mul_hi_i32_i24_e32 v155, s28, v152
	v_mul_i32_i24_e32 v154, s28, v152
	v_lshl_add_u64 v[154:155], v[154:155], 1, s[26:27]
	v_lshl_add_u64 v[154:155], v[130:131], 1, v[154:155]
	v_lshl_add_u64 v[156:157], v[154:155], 0, v[150:151]
	v_cvt_pk_bf16_f32 v120, v120, v121
	v_cvt_pk_bf16_f32 v121, v122, v123
	v_cvt_pk_bf16_f32 v122, v112, v113
	v_cvt_pk_bf16_f32 v123, v114, v115
	s_nop 1
	v_permlane16_swap_b32_e32 v120, v122
	v_permlane16_swap_b32_e32 v121, v123
	global_store_dwordx4 v[156:157], v[120:123], off
	v_cvt_pk_bf16_f32 v104, v104, v105
	v_cvt_pk_bf16_f32 v105, v106, v107
	v_cvt_pk_bf16_f32 v106, v92, v93
	v_cvt_pk_bf16_f32 v107, v94, v95
	s_nop 1
	v_permlane16_swap_b32_e32 v104, v106
	v_permlane16_swap_b32_e32 v105, v107
	global_store_dwordx4 v[156:157], v[104:107], off offset:64
	v_cvt_pk_bf16_f32 v56, v56, v57
	v_cvt_pk_bf16_f32 v57, v58, v59
	v_cvt_pk_bf16_f32 v58, v48, v49
	v_cvt_pk_bf16_f32 v59, v50, v51
	s_nop 1
	v_permlane16_swap_b32_e32 v56, v58
	v_permlane16_swap_b32_e32 v57, v59
	global_store_dwordx4 v[156:157], v[56:59], off offset:256
	v_cvt_pk_bf16_f32 v40, v40, v41
	v_cvt_pk_bf16_f32 v41, v42, v43
	v_cvt_pk_bf16_f32 v42, v28, v29
	v_cvt_pk_bf16_f32 v43, v30, v31
	s_nop 1
	v_permlane16_swap_b32_e32 v40, v42
	v_permlane16_swap_b32_e32 v41, v43
	global_store_dwordx4 v[156:157], v[40:43], off offset:320
	v_or_b32_e32 v152, 0x80, v128
	v_mul_hi_i32_i24_e32 v155, s28, v152
	v_mul_i32_i24_e32 v154, s28, v152
	v_lshl_add_u64 v[154:155], v[154:155], 1, s[26:27]
	v_lshl_add_u64 v[154:155], v[130:131], 1, v[154:155]
	v_lshl_add_u64 v[156:157], v[154:155], 0, v[150:151]
	v_cvt_pk_bf16_f32 v96, v96, v97
	v_cvt_pk_bf16_f32 v97, v98, v99
	v_cvt_pk_bf16_f32 v98, v84, v85
	v_cvt_pk_bf16_f32 v99, v86, v87
	s_nop 1
	v_permlane16_swap_b32_e32 v96, v98
	v_permlane16_swap_b32_e32 v97, v99
	global_store_dwordx4 v[156:157], v[96:99], off
	v_cvt_pk_bf16_f32 v76, v76, v77
	v_cvt_pk_bf16_f32 v77, v78, v79
	v_cvt_pk_bf16_f32 v78, v68, v69
	v_cvt_pk_bf16_f32 v79, v70, v71
	s_nop 1
	v_permlane16_swap_b32_e32 v76, v78
	v_permlane16_swap_b32_e32 v77, v79
	global_store_dwordx4 v[156:157], v[76:79], off offset:64
	v_cvt_pk_bf16_f32 v32, v32, v33
	v_cvt_pk_bf16_f32 v33, v34, v35
	v_cvt_pk_bf16_f32 v34, v20, v21
	v_cvt_pk_bf16_f32 v35, v22, v23
	s_nop 1
	v_permlane16_swap_b32_e32 v32, v34
	v_permlane16_swap_b32_e32 v33, v35
	global_store_dwordx4 v[156:157], v[32:35], off offset:256
	v_cvt_pk_bf16_f32 v12, v12, v13
	v_cvt_pk_bf16_f32 v13, v14, v15
	v_cvt_pk_bf16_f32 v14, v4, v5
	v_cvt_pk_bf16_f32 v15, v6, v7
	s_nop 1
	v_permlane16_swap_b32_e32 v12, v14
	v_permlane16_swap_b32_e32 v13, v15
	global_store_dwordx4 v[156:157], v[12:15], off offset:320
	v_or_b32_e32 v152, 0x90, v128
	v_mul_hi_i32_i24_e32 v155, s28, v152
	v_mul_i32_i24_e32 v154, s28, v152
	v_lshl_add_u64 v[154:155], v[154:155], 1, s[26:27]
	v_lshl_add_u64 v[154:155], v[130:131], 1, v[154:155]
	v_lshl_add_u64 v[156:157], v[154:155], 0, v[150:151]
	v_cvt_pk_bf16_f32 v88, v88, v89
	v_cvt_pk_bf16_f32 v89, v90, v91
	v_cvt_pk_bf16_f32 v90, v80, v81
	v_cvt_pk_bf16_f32 v91, v82, v83
	s_nop 1
	v_permlane16_swap_b32_e32 v88, v90
	v_permlane16_swap_b32_e32 v89, v91
	global_store_dwordx4 v[156:157], v[88:91], off
	v_cvt_pk_bf16_f32 v72, v72, v73
	v_cvt_pk_bf16_f32 v73, v74, v75
	v_cvt_pk_bf16_f32 v74, v64, v65
	v_cvt_pk_bf16_f32 v75, v66, v67
	s_nop 1
	v_permlane16_swap_b32_e32 v72, v74
	v_permlane16_swap_b32_e32 v73, v75
	global_store_dwordx4 v[156:157], v[72:75], off offset:64
	v_cvt_pk_bf16_f32 v24, v24, v25
	v_cvt_pk_bf16_f32 v25, v26, v27
	v_cvt_pk_bf16_f32 v26, v16, v17
	v_cvt_pk_bf16_f32 v27, v18, v19
	s_nop 1
	v_permlane16_swap_b32_e32 v24, v26
	v_permlane16_swap_b32_e32 v25, v27
	global_store_dwordx4 v[156:157], v[24:27], off offset:256
	v_cvt_pk_bf16_f32 v8, v8, v9
	v_cvt_pk_bf16_f32 v9, v10, v11
	v_cvt_pk_bf16_f32 v10, v0, v1
	v_cvt_pk_bf16_f32 v11, v2, v3
	s_nop 1
	v_permlane16_swap_b32_e32 v8, v10
	v_permlane16_swap_b32_e32 v9, v11
	global_store_dwordx4 v[156:157], v[8:11], off offset:320
	s_add_i32 s51, s51, s91
	s_cmpk_lt_i32 s51, 0xc00
	s_cbranch_scc0 .LBB0_325
	s_branch .LBB0_250
	v_cndmask_b32_e64 v128, 0, 1, s[34:35]
	v_cmp_ne_u32_e64 s[0:1], 1, v128
	s_andn2_b64 vcc, exec, s[34:35]
	v_mbcnt_lo_u32_b32 v128, -1, 0
	v_mbcnt_hi_u32_b32 v128, -1, v128
	s_cbranch_vccnz .LBB0_263
	v_mul_f32_e32 v130, 0xbfb8aa3b, v124
	v_mul_f32_e32 v131, 0xbfb8aa3b, v125
	v_mul_f32_e32 v132, 0xbfb8aa3b, v126
	v_mul_f32_e32 v133, 0xbfb8aa3b, v127
	v_exp_f32_e32 v130, v130
	v_exp_f32_e32 v131, v131
	v_exp_f32_e32 v132, v132
	v_exp_f32_e32 v133, v133
	v_add_f32_e32 v130, 1.0, v130
	v_add_f32_e32 v131, 1.0, v131
	v_add_f32_e32 v132, 1.0, v132
	v_add_f32_e32 v133, 1.0, v133
	v_rcp_f32_e32 v130, v130
	v_rcp_f32_e32 v132, v132
	v_rcp_f32_e32 v133, v133
	v_rcp_f32_e32 v131, v131
	v_pk_mul_f32 v[126:127], v[126:127], v[132:133]
	v_pk_mul_f32 v[124:125], v[124:125], v[130:131]
